# XCD row ownership for all GEMMs incl. QKV, attention units placed on the XCD owning their token block, up-GEMM column rounds reversed so down reads the freshest columns first
# speedup vs baseline: 1.0135x; 1.0135x over previous
; #define PG8_STAGE(bufoff, gbase, voff) do { _Pragma("unroll") for (int _i = 0; _i < 2; ++_i) \
;         __builtin_amdgcn_global_load_lds((const unsigned*)((const char*)(gbase) + (voff)[_i]), (LAS unsigned*)(lds + (bufoff) + ldsw + _i * 8192), 16, 0, 0); } while (0)
;     __device__ bool next(int i, Unit& u) const {
;         const long L = (long)i * G + c; if (L >= nwg) return false;
;         int wgid = (int)L; { const int q = nwg / NXCD, r = nwg % NXCD, xcd = wgid % NXCD, off = wgid / NXCD; wgid = (xcd < r ? xcd * (q + 1) : r * (q + 1) + (xcd - r) * q) + off; }
;         const int nig = WGM * nN, gid = wgid / nig, fm = gid * WGM, gsz = (nM - fm) < WGM ? (nM - fm) : WGM;
;         u.pm = fm + ((wgid % nig) % gsz); u.pn = (wgid % nig) / gsz; return true;
; template <class Epi>
; __device__ __forceinline__ void gemm_phase(LAS unsigned char* lds, const Gemm g, const StaticOrder& S, const Epi& E) {
;     ...
;     for (int i = 0; i < 2; ++i) { int R, C; stage_rc(tid * 16 + i * 8192, R, C); const int Rb = Epi::PERM ? ((R & ~31) + perm32(R & 31)) : R;
;         voffA[i] = (unsigned)(R * g.lda + C) * 2u; voffB[i] = (unsigned)(Rb * g.ldb + C) * 2u; }
;     const size_t kstep = (size_t)(BK * 2);
;     const size_t hstepA = (size_t)HALF * g.lda * 2, hstepB = (size_t)HALF * g.ldb * 2;
;     const size_t tstepA = 2 * hstepA, tstepB = 2 * hstepB;
;     const unsigned ldsw = (unsigned)wid * 1024u;
;     const int aoff = lds_byte(wr * 64 + fr, fq * 8), boff = lds_byte(wc * 32 + fr, fq * 8);
;     ...
;     Unit cur, nxt; int ui = 0;
;     if (!S.next(0, cur)) return;
;     f32x4 acc[2][2][4][2];
; #pragma unroll
;     for (int a = 0; a < 2; ++a)
; #pragma unroll
;         for (int b = 0; b < 2; ++b)
; #pragma unroll
;             for (int m = 0; m < 4; ++m)
; #pragma unroll
;                 for (int n = 0; n < 2; ++n) acc[a][b][m][n] = (f32x4){0.f, 0.f, 0.f, 0.f};
;     bf16x8 At[4][2], B0[2][2], B1[2][2];
;     const char* cA = PG8_UA(cur); const char* cB = PG8_UB(cur);
;     PG8_STAGE(PG8_SB(0, 0), cB, voffB); PG8_STAGE(PG8_SB(0, 1), cB + hstepB, voffB); PG8_STAGE(PG8_SA(0, 0), cA, voffA); PG8_STAGE(PG8_SA(0, 1), cA + hstepA, voffA);
;     if (wr == 1) PG8_BAR;
;     PG8_WAIT_V(2); PG8_BAR;
;     PG8_STAGE(PG8_SB(1, 0), cB + kstep, voffB); PG8_STAGE(PG8_SA(1, 0), cA + kstep, voffA); PG8_STAGE(PG8_SB(1, 1), cB + hstepB + kstep, voffB);
;     PG8_WAIT_V(6); PG8_BAR;
.LBB0_1402:
	v_readlane_b32 s0, v255, 42
	v_readlane_b32 s1, v255, 43
	s_mov_b32 s1, s43
	v_writelane_b32 v255, s0, 42
	s_and_b64 vcc, exec, s[34:35]
	s_nop 0
	v_writelane_b32 v255, s1, 43
	s_cbranch_vccz .LBB0_2113
	s_mov_b32 s0, s78
	s_mov_b32 s1, s74
	v_mov_b32_e32 v1, v246
	s_cmpk_gt_i32 s1, 0x13f
	v_readfirstlane_b32 s3, v1
	s_cbranch_scc1 .LBB0_1421
	v_lshlrev_b32_e32 v2, 4, v1
	s_waitcnt lgkmcnt(0)
	v_add_u32_e32 v3, 0x2000, v2
	v_ashrrev_i32_e32 v4, 31, v3
	v_lshrrev_b32_e32 v4, 22, v4
	v_add_u32_e32 v4, v3, v4
	v_ashrrev_i32_e32 v10, 10, v4
	v_mul_i32_i24_e32 v4, 0x400, v10
	v_sub_u32_e32 v3, v3, v4
	v_lshrrev_b32_e32 v4, 4, v3
	v_bitop3_b32 v3, v4, v3, 32 bitop3:0x6c
	v_ashrrev_i32_e32 v4, 31, v3
	v_readlane_b32 s4, v255, 37
	v_lshrrev_b32_e32 v4, 26, v4
	v_readlane_b32 s5, v255, 38
	v_add_u32_e32 v4, v3, v4
	v_lshlrev_b32_e32 v5, 3, v10
	s_and_b64 s[4:5], s[4:5], exec
	v_ashrrev_i32_e32 v11, 6, v4
	v_and_b32_e32 v5, -16, v5
	s_cselect_b32 s4, 0, 0x4400000
	v_readlane_b32 s6, v254, 0
	v_add_u32_e32 v5, v11, v5
	s_add_u32 s26, s6, s4
	v_and_b32_e32 v6, 3, v11
	s_mov_b32 s4, 0xfffe0
	v_lshrrev_b32_e32 v7, 2, v5
	v_lshlrev_b32_e32 v8, 1, v5
	v_and_or_b32 v6, v5, s4, v6
	v_and_b32_e32 v7, 4, v7
	v_and_b32_e32 v8, 24, v8
	v_and_b32_e32 v4, 0xc0, v4
	v_or3_b32 v6, v6, v7, v8
	v_sub_u32_e32 v3, v3, v4
	v_mov_b32_e32 v8, 1
	v_lshlrev_b32_e32 v7, 5, v10
	v_ashrrev_i16_sdwa v3, v8, sext(v3) dst_sel:DWORD dst_unused:UNUSED_PAD src0_sel:DWORD src1_sel:BYTE_0
	v_and_b32_e32 v7, 32, v7
	v_bfe_i32 v12, v3, 0, 16
	v_add_lshl_u32 v3, v7, v12, 1
	v_lshl_add_u32 v146, v6, 12, v3
	v_lshl_add_u32 v148, v5, 12, v3
	v_bfe_i32 v3, v1, 27, 1
	v_lshrrev_b32_e32 v3, 22, v3
	v_add_u32_e32 v3, v2, v3
	v_and_b32_e32 v3, 0xfffffc00, v3
	v_sub_u32_e32 v2, v2, v3
	v_lshrrev_b32_e32 v3, 4, v2
	v_bitop3_b32 v3, v3, v2, 32 bitop3:0x6c
	v_ashrrev_i32_e32 v2, 31, v2
	v_lshrrev_b32_e32 v2, 26, v2
	v_add_u32_e32 v2, v3, v2
	v_ashrrev_i32_e32 v13, 6, v2
	v_ashrrev_i32_e32 v2, 31, v1
	v_lshrrev_b32_e32 v2, 26, v2
	v_add_u32_e32 v2, v1, v2
	v_ashrrev_i32_e32 v14, 6, v2
	v_lshlrev_b32_e32 v2, 3, v14
	v_readlane_b32 s7, v254, 1
	v_and_b32_e32 v2, -16, v2
	s_addc_u32 s27, s7, 0
	v_add_u32_e32 v2, v13, v2
	v_and_b32_e32 v4, 3, v13
	s_ashr_i32 s29, s1, 31
	v_and_or_b32 v4, v2, s4, v4
	s_lshr_b32 s4, s29, 29
	s_add_i32 s4, s1, s4
	s_ashr_i32 s5, s3, 6
	s_ashr_i32 s6, s4, 3
	s_and_b32 s4, s4, -8
	s_ashr_i32 s10, s3, 8
	s_lshl_b32 s28, s5, 10
	s_sub_i32 s4, s1, s4
	s_cmp_lt_i32 s4, 0
	s_cselect_b32 s7, 41, 40
	s_mul_i32 s4, s4, s7
	s_add_i32 s4, s4, s6
	s_mul_i32 s100, s4, 0xcccd
	s_lshr_b32 s100, s100, 21
	s_mul_i32 s101, s100, 40
	s_sub_i32 s101, s4, s101
	s_lshr_b32 s4, s100, 1
	s_mul_i32 s4, s4, 0x50
	s_and_b32 s100, s100, 1
	s_lshl_b32 s100, s100, 2
	s_add_i32 s4, s4, s100
	s_and_b32 s100, s101, 3
	s_add_i32 s4, s4, s100
	s_lshr_b32 s101, s101, 2
	s_lshl_b32 s101, s101, 3
	s_add_i32 s4, s4, s101
	s_mul_hi_i32 s6, s4, 0x66666667
	s_lshr_b32 s7, s6, 31
	s_ashr_i32 s6, s6, 5
	s_add_i32 s6, s6, s7
	s_lshl_b32 s7, s6, 3
	s_mulk_i32 s6, 0x50
	s_sub_i32 s6, s4, s6
	s_bfe_i32 s4, s6, 0x80000
	s_bfe_u32 s4, s4, 0x3000c
	s_add_i32 s8, s6, s4
	s_bfe_i32 s4, s8, 0x80000
	s_and_b32 s8, s8, 0xf8
	v_lshrrev_b32_e32 v5, 2, v2
	v_lshlrev_b32_e32 v6, 1, v2
	s_sub_i32 s6, s6, s8
	v_and_b32_e32 v5, 4, v5
	v_and_b32_e32 v6, 24, v6
	s_sext_i32_i16 s4, s4
	s_sext_i32_i8 s6, s6
	v_or3_b32 v4, v4, v5, v6
	v_mul_i32_i24_e32 v6, 64, v13
	s_lshr_b32 s4, s4, 3
	s_add_i32 s6, s7, s6
	v_sub_u32_e32 v3, v3, v6
	s_ashr_i32 s7, s6, 31
	s_bfe_i64 s[12:13], s[4:5], 0x100000
	v_lshlrev_b32_e32 v5, 5, v14
	v_ashrrev_i16_sdwa v3, v8, sext(v3) dst_sel:DWORD dst_unused:UNUSED_PAD src0_sel:DWORD src1_sel:BYTE_0
	s_lshl_b64 s[8:9], s[6:7], 20
	s_lshl_b64 s[12:13], s[12:13], 20
	v_and_b32_e32 v5, 32, v5
	v_bfe_i32 v15, v3, 0, 16
	s_add_u32 s14, s26, s12
	v_add_lshl_u32 v3, v5, v15, 1
	s_addc_u32 s15, s27, s13
	s_add_i32 s30, s28, 0
	v_lshl_add_u32 v150, v4, 12, v3
	s_add_i32 m0, s30, 0x10000
	v_lshl_add_u32 v152, v2, 12, v3
	global_load_lds_dwordx4 v150, s[14:15]
	s_add_i32 m0, s30, 0x12000
	s_add_u32 s12, s14, 0x80000
	global_load_lds_dwordx4 v146, s[14:15]
	s_addc_u32 s13, s15, 0
	s_add_i32 m0, s30, 0x14000
	v_mov_b32_e32 v151, v0
	global_load_lds_dwordx4 v150, s[12:13]
	s_add_i32 m0, s30, 0x16000
	s_add_u32 s22, s54, s8
	s_addc_u32 s23, s55, s9
	s_add_i32 s31, s30, 0x2000
	global_load_lds_dwordx4 v146, s[12:13]
	s_mov_b32 m0, s30
	s_add_u32 s8, s22, 0x80000
	global_load_lds_dwordx4 v152, s[22:23]
	s_mov_b32 m0, s31
	s_addc_u32 s9, s23, 0
	s_add_i32 s33, s30, 0x4000
	global_load_lds_dwordx4 v148, s[22:23]
	s_mov_b32 m0, s33
	s_add_i32 s34, s30, 0x6000
	global_load_lds_dwordx4 v152, s[8:9]
	s_mov_b32 m0, s34
	v_mov_b32_e32 v147, v0
	global_load_lds_dwordx4 v148, s[8:9]
	v_mov_b32_e32 v153, v0
	v_mov_b32_e32 v149, v0
	s_cmp_eq_u32 s10, 1
	v_lshl_add_u64 v[8:9], s[14:15], 0, v[150:151]
	v_lshl_add_u64 v[6:7], s[14:15], 0, v[146:147]
	v_lshl_add_u64 v[2:3], s[22:23], 0, v[152:153]
	s_cselect_b64 s[8:9], -1, 0
	s_cmp_lg_u32 s10, 1
	v_lshl_add_u64 v[4:5], s[22:23], 0, v[148:149]
	s_cbranch_scc1 .LBB0_1406
	s_barrier

;     __device__ bool next(int i, Unit& u) const {
;         const long L = (long)i * G + c; if (L >= nwg) return false;
;         int wgid = (int)L; { const int q = nwg / NXCD, r = nwg % NXCD, xcd = wgid % NXCD, off = wgid / NXCD; wgid = (xcd < r ? xcd * (q + 1) : r * (q + 1) + (xcd - r) * q) + off; }
;         const int nig = WGM * nN, gid = wgid / nig, fm = gid * WGM, gsz = (nM - fm) < WGM ? (nM - fm) : WGM;
;         u.pm = fm + ((wgid % nig) % gsz); u.pn = (wgid % nig) / gsz; return true;
.LBB0_1409:
	s_add_i32 s53, s53, 1
	s_mul_i32 s3, s53, s52
	s_mul_hi_u32 s4, s53, s0
	s_add_i32 s4, s4, s3
	s_mul_i32 s3, s53, s0
	s_add_u32 s18, s3, s1
	s_addc_u32 s19, s4, s29
	v_mov_b64_e32 v[2:3], 0x140
	v_cmp_lt_i64_e64 s[4:5], s[18:19], v[2:3]
	v_mov_b64_e32 v[2:3], 0x13f
	v_cmp_gt_i64_e32 vcc, s[18:19], v[2:3]
	s_cbranch_vccnz .LBB0_1411
	s_ashr_i32 s3, s18, 31
	s_lshr_b32 s3, s3, 29
	s_add_i32 s3, s18, s3
	s_ashr_i32 s7, s3, 3
	s_and_b32 s3, s3, -8
	s_sub_i32 s3, s18, s3
	s_cmp_lt_i32 s3, 0
	s_cselect_b32 s12, 41, 40
	s_mul_i32 s3, s3, s12
	s_add_i32 s3, s3, s7
	s_mul_i32 s100, s3, 0xcccd
	s_lshr_b32 s100, s100, 21
	s_mul_i32 s101, s100, 40
	s_sub_i32 s101, s3, s101
	s_lshr_b32 s3, s100, 1
	s_mul_i32 s3, s3, 0x50
	s_and_b32 s100, s100, 1
	s_lshl_b32 s100, s100, 2
	s_add_i32 s3, s3, s100
	s_and_b32 s100, s101, 3
	s_add_i32 s3, s3, s100
	s_lshr_b32 s101, s101, 2
	s_lshl_b32 s101, s101, 3
	s_add_i32 s3, s3, s101
	s_mul_hi_i32 s7, s3, 0x66666667
	s_lshr_b32 s12, s7, 31
	s_ashr_i32 s7, s7, 5
	s_add_i32 s7, s7, s12
	s_lshl_b32 s13, s7, 3
	s_sub_i32 s12, 32, s13
	s_min_i32 s16, s12, 8
	s_abs_i32 s12, s16
	v_cvt_f32_u32_e32 v2, s12
	s_sub_i32 s18, 0, s12
	s_mulk_i32 s7, 0x50
	s_sub_i32 s3, s3, s7
	v_rcp_iflag_f32_e32 v2, v2
	s_abs_i32 s7, s3
	s_xor_b32 s17, s3, s16
	s_ashr_i32 s17, s17, 31
	v_mul_f32_e32 v2, 0x4f7ffffe, v2
	v_cvt_u32_f32_e32 v2, v2
	s_nop 0
	v_readfirstlane_b32 s19, v2
	s_mul_i32 s18, s18, s19
	s_mul_hi_u32 s18, s19, s18
	s_add_i32 s19, s19, s18
	s_mul_hi_u32 s18, s7, s19
	s_mul_i32 s19, s18, s12
	s_sub_i32 s7, s7, s19
	s_add_i32 s20, s18, 1
	s_sub_i32 s19, s7, s12
	s_cmp_ge_u32 s7, s12
	s_cselect_b32 s18, s20, s18
	s_cselect_b32 s7, s19, s7
	s_add_i32 s19, s18, 1
	s_cmp_ge_u32 s7, s12
	s_cselect_b32 s7, s19, s18
	s_xor_b32 s7, s7, s17
	s_sub_i32 s12, s7, s17
	s_mul_i32 s7, s12, s16
	s_sub_i32 s3, s3, s7
	s_add_i32 s16, s13, s3

; __device__ __forceinline__ void attn_phase(LAS unsigned char* lds, const bf16_t* QKV, const int* positions, const float* qn, const float* kn, const float* sinks, bf16_t* AO, int G, int bid) {
;     const int tid = launder(threadIdx.x), lane = tid & 63, wave = __builtin_amdgcn_readfirstlane(tid >> 6);
;     const int fr = lane & 15, fq = lane >> 4;
;     for (int unit = bid; unit < (T / 128) * 4; unit += G) {
;         const int nb = unit >> 2, hk = unit & 3;
;         {
;             const int kk = tid >> 1, half = tid & 1; const int tok = (nb - 1) * 128 + kk;
;             u32x4 kraw[4], vraw[4];
;             if (tok >= 0) {
;                 const u32x4* kp = (const u32x4*)(QKV + (size_t)tok * NQKV + 2048 + hk * 64 + half * 32);
;                 const u32x4* vp = (const u32x4*)(QKV + (size_t)tok * NQKV + 2304 + hk * 64 + half * 32);
; #pragma unroll
;                 for (int i = 0; i < 4; ++i) { kraw[i] = kp[i]; vraw[i] = vp[i]; }
;             } else {
; #pragma unroll
;                 for (int i = 0; i < 4; ++i) { kraw[i] = (u32x4){0u, 0u, 0u, 0u}; vraw[i] = (u32x4){0u, 0u, 0u, 0u}; }
;             }
;             float ss = 0.f;
; #pragma unroll
;             for (int i = 0; i < 4; ++i)
; #pragma unroll
;                 for (int j = 0; j < 4; ++j) { const float a = bflo(kraw[i][j]), b = bfhi(kraw[i][j]); ss += a * a + b * b; }
;             ss += shx(ss, 1, lane);
;             const float rstd = rsqrtf(ss * (1.0f / 64.0f) + EPS);
;             LAS unsigned char* krow = lds + ATT_KS + kk * KS_STRIDE + half * 64;
; #pragma unroll
;             for (int i = 0; i < 4; ++i) { u32x4 w;
; #pragma unroll
;                 for (int j = 0; j < 4; ++j) { const int d = half * 32 + i * 8 + j * 2; w[j] = cvt_pk_bf16(bflo(kraw[i][j]) * rstd * kn[d], bfhi(kraw[i][j]) * rstd * kn[d + 1]); }
;                 *(LAS u32x4*)(krow + i * 16) = w; }
; #pragma unroll
;             for (int i = 0; i < 4; ++i)
; #pragma unroll
;                 for (int j = 0; j < 4; ++j) { const int d = half * 32 + i * 8 + j * 2;
;                     *(LAS unsigned short*)(lds + ATT_VT + d * VT_STRIDE + kk * 2) = (unsigned short)(vraw[i][j] & 0xffffu);
;                     *(LAS unsigned short*)(lds + ATT_VT + (d + 1) * VT_STRIDE + kk * 2) = (unsigned short)(vraw[i][j] >> 16); }
;             if (half == 0) ((LAS int*)(lds + ATT_KP))[kk] = tok >= 0 ? positions[tok] : PAD_POS;
.LBB0_1858:
	s_or_b64 exec, exec, s[4:5]
	v_readlane_b32 s0, v254, 52
	v_mov_b32_e32 v1, v246
	v_readlane_b32 s1, v254, 53
	s_waitcnt lgkmcnt(0)
	s_barrier
	s_andn2_b64 vcc, exec, s[0:1]
	v_readfirstlane_b32 s0, v1
	s_cbranch_vccnz .LBB0_1964
	v_readlane_b32 s1, v255, 39
	s_lshl_b32 s1, s1, 3
	s_load_dwordx4 s[8:11], s[76:77], s1 offset:0x10
	s_load_dwordx2 s[16:17], s[76:77], s1 offset:0x20
	s_ashr_i32 s14, s0, 6
	v_ashrrev_i32_e32 v4, 1, v1
	s_movk_i32 s0, 0x90
	v_and_b32_e32 v3, 63, v1
	v_and_b32_e32 v10, 1, v1
	v_mul_lo_u32 v5, v4, s0
	v_readlane_b32 s0, v255, 11
	v_lshlrev_b32_e32 v2, 5, v10
	v_lshlrev_b32_e32 v3, 2, v3
	v_lshl_add_u32 v116, v4, 2, s0
	s_movk_i32 s0, 0x4200
	v_and_b32_e32 v112, 15, v1
	v_bfe_u32 v7, v1, 4, 2
	v_xor_b32_e32 v114, 4, v3
	v_and_b32_e32 v115, -2, v1
	v_xor_b32_e32 v117, 64, v3
	v_xor_b32_e32 v118, 0x80, v3
	v_and_b32_e32 v6, 48, v1
	v_lshlrev_b32_e32 v8, 7, v10
	v_mov_b32_e32 v9, v0
	v_or_b32_e32 v1, 2, v2
	v_mad_u32_u24 v3, v10, s0, 0
	s_movk_i32 s0, 0x210
	v_add_u32_e32 v113, 0xffffff80, v4
	v_add_u32_e32 v11, 0, v5
	v_lshlrev_b32_e32 v4, 3, v7
	v_mov_b32_e32 v5, v0
	s_waitcnt lgkmcnt(0)
	v_lshl_add_u64 v[94:95], s[10:11], 0, v[8:9]
	v_mad_u32_u24 v120, v1, s0, 0
	v_lshlrev_b32_e32 v8, 5, v7
	v_mul_u32_u24_e32 v7, 0x210, v112
	v_lshlrev_b32_e32 v12, 6, v10
	v_cmp_eq_u32_e64 s[4:5], 0, v10
	v_add_u32_e32 v119, 0, v6
	v_lshl_add_u64 v[92:93], s[66:67], 0, v[4:5]
	v_add_u32_e32 v1, 0x420, v120
	v_add_u32_e32 v5, 0x840, v120
	v_add_u32_e32 v10, 0xc60, v120
	v_add_u32_e32 v13, 0x1080, v120
	v_add_u32_e32 v14, 0x14a0, v120
	v_add_u32_e32 v15, 0x18c0, v120
	v_add_u32_e32 v16, 0x1ce0, v120
	v_add_u32_e32 v17, 0x2100, v120
	v_add_u32_e32 v18, 0x2520, v120
	v_add_u32_e32 v19, 0x2940, v120
	v_add_u32_e32 v20, 0x2d60, v120
	v_add_u32_e32 v21, 0x3180, v120
	v_add_u32_e32 v22, 0x35a0, v120
	v_add_u32_e32 v23, 0x39c0, v120
	v_lshl_add_u64 v[96:97], s[8:9], 0, v[8:9]
	v_mul_u32_u24_e32 v8, 0x90, v112
	v_add3_u32 v121, 0, v4, v7
	v_mov_b32_e32 v7, v0
	v_lshl_add_u64 v[98:99], s[58:59], 0, v[6:7]
	v_lshlrev_b32_e32 v100, 1, v2
	v_add_u32_e32 v122, v11, v12
	v_add_u32_e32 v123, v3, v115
	v_add_u32_e32 v124, v1, v115
	v_add_u32_e32 v125, v5, v115
	v_add_u32_e32 v126, v10, v115
	v_add_u32_e32 v127, v13, v115
	v_add_u32_e32 v128, v14, v115
	v_add_u32_e32 v129, v15, v115
	v_add_u32_e32 v130, v16, v115
	v_add_u32_e32 v131, v17, v115
	v_add_u32_e32 v132, v18, v115
	v_add_u32_e32 v133, v19, v115
	v_add_u32_e32 v134, v20, v115
	v_add_u32_e32 v135, v21, v115
	v_add_u32_e32 v136, v22, v115
	v_add_u32_e32 v137, v23, v115
	v_lshlrev_b32_e32 v102, 1, v4
	v_add_u32_e32 v138, v119, v8
	s_mov_b32 s18, s74
	s_cmp_lg_u32 s78, 0x100
	s_cbranch_scc1 .Lattn_noperm
	s_and_b32 s18, s74, 7
	s_lshl_b32 s18, s18, 5
	s_lshr_b32 s15, s74, 3
	s_or_b32 s18, s18, s15
.Lattn_noperm:
	s_lshl_b32 s15, s18, 5
	s_branch .LBB0_1861

; #define PG8_STAGE(bufoff, gbase, voff) do { _Pragma("unroll") for (int _i = 0; _i < 2; ++_i) \
;         __builtin_amdgcn_global_load_lds((const unsigned*)((const char*)(gbase) + (voff)[_i]), (LAS unsigned*)(lds + (bufoff) + ldsw + _i * 8192), 16, 0, 0); } while (0)
;     __device__ bool next(int i, Unit& u) const {
;         const long L = (long)i * G + c; if (L >= nwg) return false;
;         int wgid = (int)L; { const int q = nwg / NXCD, r = nwg % NXCD, xcd = wgid % NXCD, off = wgid / NXCD; wgid = (xcd < r ? xcd * (q + 1) : r * (q + 1) + (xcd - r) * q) + off; }
;         const int nig = WGM * nN, gid = wgid / nig, fm = gid * WGM, gsz = (nM - fm) < WGM ? (nM - fm) : WGM;
;         u.pm = fm + ((wgid % nig) % gsz); u.pn = (wgid % nig) / gsz; return true;
; template <class Epi>
; __device__ __forceinline__ void gemm_phase(LAS unsigned char* lds, const Gemm g, const StaticOrder& S, const Epi& E) {
;     ...
;     for (int i = 0; i < 2; ++i) { int R, C; stage_rc(tid * 16 + i * 8192, R, C); const int Rb = Epi::PERM ? ((R & ~31) + perm32(R & 31)) : R;
;         voffA[i] = (unsigned)(R * g.lda + C) * 2u; voffB[i] = (unsigned)(Rb * g.ldb + C) * 2u; }
;     const size_t kstep = (size_t)(BK * 2);
;     const size_t hstepA = (size_t)HALF * g.lda * 2, hstepB = (size_t)HALF * g.ldb * 2;
;     const size_t tstepA = 2 * hstepA, tstepB = 2 * hstepB;
;     const unsigned ldsw = (unsigned)wid * 1024u;
;     const int aoff = lds_byte(wr * 64 + fr, fq * 8), boff = lds_byte(wc * 32 + fr, fq * 8);
;     ...
;     Unit cur, nxt; int ui = 0;
;     if (!S.next(0, cur)) return;
;     f32x4 acc[2][2][4][2];
; #pragma unroll
;     for (int a = 0; a < 2; ++a)
; #pragma unroll
;         for (int b = 0; b < 2; ++b)
; #pragma unroll
;             for (int m = 0; m < 4; ++m)
; #pragma unroll
;                 for (int n = 0; n < 2; ++n) acc[a][b][m][n] = (f32x4){0.f, 0.f, 0.f, 0.f};
;     bf16x8 At[4][2], B0[2][2], B1[2][2];
;     const char* cA = PG8_UA(cur); const char* cB = PG8_UB(cur);
;     PG8_STAGE(PG8_SB(0, 0), cB, voffB); PG8_STAGE(PG8_SB(0, 1), cB + hstepB, voffB); PG8_STAGE(PG8_SA(0, 0), cA, voffA); PG8_STAGE(PG8_SA(0, 1), cA + hstepA, voffA);
;     if (wr == 1) PG8_BAR;
;     PG8_WAIT_V(2); PG8_BAR;
;     PG8_STAGE(PG8_SB(1, 0), cB + kstep, voffB); PG8_STAGE(PG8_SA(1, 0), cA + kstep, voffA); PG8_STAGE(PG8_SB(1, 1), cB + hstepB + kstep, voffB);
;     PG8_WAIT_V(6); PG8_BAR;
.LBB0_2118:
	s_waitcnt lgkmcnt(0)
	v_ashrrev_i32_e32 v3, 31, v1
	v_lshrrev_b32_e32 v3, 26, v3
	v_add_u32_e32 v3, v1, v3
	v_ashrrev_i32_e32 v10, 6, v3
	v_bfe_i32 v3, v1, 27, 1
	v_lshlrev_b32_e32 v2, 4, v1
	v_lshrrev_b32_e32 v3, 22, v3
	v_add_u32_e32 v3, v2, v3
	v_and_b32_e32 v3, 0xfffffc00, v3
	v_sub_u32_e32 v3, v2, v3
	v_lshrrev_b32_e32 v4, 4, v3
	v_bitop3_b32 v4, v4, v3, 32 bitop3:0x6c
	v_ashrrev_i32_e32 v3, 31, v3
	v_lshrrev_b32_e32 v3, 26, v3
	v_add_u32_e32 v3, v4, v3
	v_ashrrev_i32_e32 v11, 6, v3
	v_lshlrev_b32_e32 v5, 3, v10
	v_mul_i32_i24_e32 v6, 64, v11
	v_and_b32_e32 v5, -16, v5
	v_sub_u32_e32 v4, v4, v6
	v_mov_b32_e32 v8, 1
	v_add_u32_e32 v3, v11, v5
	v_lshlrev_b32_e32 v5, 5, v10
	v_ashrrev_i16_sdwa v4, v8, sext(v4) dst_sel:DWORD dst_unused:UNUSED_PAD src0_sel:DWORD src1_sel:BYTE_0
	v_and_b32_e32 v5, 32, v5
	v_bfe_i32 v12, v4, 0, 16
	v_and_b32_e32 v7, 3, v11
	s_mov_b32 s1, 0xfffe0
	v_add_lshl_u32 v5, v5, v12, 1
	v_add_u32_e32 v2, 0x2000, v2
	v_lshlrev_b32_e32 v4, 1, v3
	v_lshrrev_b32_e32 v6, 2, v3
	v_and_or_b32 v7, v3, s1, v7
	v_lshl_add_u32 v130, v3, 12, v5
	v_ashrrev_i32_e32 v3, 31, v2
	v_lshrrev_b32_e32 v3, 22, v3
	v_add_u32_e32 v3, v2, v3
	v_ashrrev_i32_e32 v13, 10, v3
	v_mul_i32_i24_e32 v3, 0x400, v13
	v_sub_u32_e32 v2, v2, v3
	v_and_b32_e32 v4, 24, v4
	v_and_b32_e32 v6, 4, v6
	v_lshrrev_b32_e32 v3, 4, v2
	v_or3_b32 v4, v7, v6, v4
	v_bitop3_b32 v2, v3, v2, 32 bitop3:0x6c
	v_lshl_add_u32 v132, v4, 12, v5
	v_ashrrev_i32_e32 v4, 31, v2
	v_lshrrev_b32_e32 v4, 26, v4
	v_lshlrev_b32_e32 v3, 3, v13
	v_add_u32_e32 v4, v2, v4
	v_and_b32_e32 v3, -16, v3
	v_ashrrev_i32_e32 v14, 6, v4
	v_add_u32_e32 v3, v14, v3
	v_and_b32_e32 v6, 3, v14
	s_add_i32 s0, s4, s0
	s_xor_b32 s0, s0, 0x60
	s_bfe_u32 s100, s0, 0x10007
	s_bfe_u32 s101, s0, 0x50002
	s_andn2_b32 s0, s0, 0xfc
	s_lshl_b32 s100, s100, 2
	s_lshl_b32 s101, s101, 3
	s_or_b32 s0, s0, s100
	s_or_b32 s0, s0, s101
	v_and_or_b32 v6, v3, s1, v6
	s_ashr_i32 s1, s0, 31
	s_lshr_b32 s1, s1, 24
	s_add_i32 s1, s0, s1
	s_ashr_i32 s4, s1, 8
	s_and_b32 s1, s1, 0xff00
	s_sub_i32 s0, s0, s1
	s_sext_i32_i16 s1, s0
	s_bfe_u32 s1, s1, 0x3001c
	s_add_i32 s1, s0, s1
	s_lshl_b32 s7, s4, 3
	s_sext_i32_i16 s4, s1
	s_and_b32 s1, s1, 0xfff8
	s_sub_i32 s0, s0, s1
	s_sext_i32_i16 s0, s0
	s_ashr_i32 s5, s3, 8
	s_lshr_b32 s4, s4, 3
	s_add_i32 s18, s7, s0
	v_and_b32_e32 v4, 0xc0, v4
	s_ashr_i32 s6, s3, 6
	s_ashr_i32 s19, s18, 31
	s_bfe_i64 s[8:9], s[4:5], 0x100000
	v_sub_u32_e32 v2, v2, v4
	s_lshl_b32 s27, s6, 10
	s_lshl_b64 s[0:1], s[18:19], 20
	s_lshl_b64 s[8:9], s[8:9], 20
	v_ashrrev_i16_sdwa v2, v8, sext(v2) dst_sel:DWORD dst_unused:UNUSED_PAD src0_sel:DWORD src1_sel:BYTE_0
	s_add_u32 s22, s88, s8
	v_lshlrev_b32_e32 v5, 5, v13
	v_bfe_i32 v15, v2, 0, 16
	v_lshlrev_b32_e32 v2, 1, v3
	v_lshrrev_b32_e32 v4, 2, v3
	s_addc_u32 s23, s89, s9
	s_add_i32 s19, s27, 0
	v_and_b32_e32 v5, 32, v5
	v_and_b32_e32 v2, 24, v2
	v_and_b32_e32 v4, 4, v4
	s_add_i32 m0, s19, 0x10000
	v_or3_b32 v2, v6, v4, v2
	v_add_lshl_u32 v4, v5, v15, 1
	global_load_lds_dwordx4 v132, s[22:23]
	s_add_i32 m0, s19, 0x12000
	v_lshl_add_u32 v136, v2, 12, v4
	s_add_u32 s8, s22, 0x80000
	global_load_lds_dwordx4 v136, s[22:23]
	s_addc_u32 s9, s23, 0
	s_add_i32 m0, s19, 0x14000
	v_lshl_add_u32 v134, v3, 12, v4
	global_load_lds_dwordx4 v132, s[8:9]
	s_add_i32 m0, s19, 0x16000
	s_add_u32 s20, s54, s0
	s_addc_u32 s21, s55, s1
	s_add_i32 s28, s19, 0x2000
	global_load_lds_dwordx4 v136, s[8:9]
	s_mov_b32 m0, s19
	s_add_u32 s0, s20, 0x80000
	global_load_lds_dwordx4 v130, s[20:21]
	s_mov_b32 m0, s28
	s_addc_u32 s1, s21, 0
	s_add_i32 s29, s19, 0x4000
	global_load_lds_dwordx4 v134, s[20:21]
	s_mov_b32 m0, s29
	s_add_i32 s30, s19, 0x6000
	global_load_lds_dwordx4 v130, s[0:1]
	s_mov_b32 m0, s30
	v_mov_b32_e32 v133, v0
	global_load_lds_dwordx4 v134, s[0:1]
	v_mov_b32_e32 v137, v0
	v_mov_b32_e32 v131, v0
	v_mov_b32_e32 v135, v0
	s_cmp_eq_u32 s5, 1
	v_lshl_add_u64 v[8:9], s[22:23], 0, v[132:133]
	v_lshl_add_u64 v[6:7], s[22:23], 0, v[136:137]
	v_lshl_add_u64 v[2:3], s[20:21], 0, v[130:131]
	s_cselect_b64 s[0:1], -1, 0
	s_cmp_lg_u32 s5, 1
	v_lshl_add_u64 v[4:5], s[20:21], 0, v[134:135]
	s_cbranch_scc1 .LBB0_2120
	s_barrier

;     __device__ bool next(int i, Unit& u) const {
;         const long L = (long)i * G + c; if (L >= nwg) return false;
;         int wgid = (int)L; { const int q = nwg / NXCD, r = nwg % NXCD, xcd = wgid % NXCD, off = wgid / NXCD; wgid = (xcd < r ? xcd * (q + 1) : r * (q + 1) + (xcd - r) * q) + off; }
;         const int nig = WGM * nN, gid = wgid / nig, fm = gid * WGM, gsz = (nM - fm) < WGM ? (nM - fm) : WGM;
;         u.pm = fm + ((wgid % nig) % gsz); u.pn = (wgid % nig) / gsz; return true;
.LBB0_2128:
	s_ashr_i32 s3, s3, 3
	s_add_i32 s3, s11, s3
	s_xor_b32 s3, s3, 0x60
	s_bfe_u32 s100, s3, 0x10007
	s_bfe_u32 s101, s3, 0x50002
	s_andn2_b32 s3, s3, 0xfc
	s_lshl_b32 s100, s100, 2
	s_lshl_b32 s101, s101, 3
	s_or_b32 s3, s3, s100
	s_or_b32 s3, s3, s101
	s_ashr_i32 s8, s3, 31
	s_lshr_b32 s8, s8, 24
	s_add_i32 s8, s3, s8
	s_ashr_i32 s9, s8, 8
	s_lshl_b32 s9, s9, 3
	s_sub_i32 s10, 32, s9
	s_min_i32 s10, s10, 8
	s_abs_i32 s11, s10
	v_cvt_f32_u32_e32 v2, s11
	s_sub_i32 s13, 0, s11
	s_and_b32 s8, s8, 0xffffff00
	s_sub_i32 s3, s3, s8
	v_rcp_iflag_f32_e32 v2, v2
	s_abs_i32 s8, s3
	s_xor_b32 s12, s3, s10
	s_ashr_i32 s12, s12, 31
	v_mul_f32_e32 v2, 0x4f7ffffe, v2
	v_cvt_u32_f32_e32 v2, v2
	s_nop 0
	v_readfirstlane_b32 s14, v2
	s_mul_i32 s13, s13, s14
	s_mul_hi_u32 s13, s14, s13
	s_add_i32 s14, s14, s13
	s_mul_hi_u32 s13, s8, s14
	s_mul_i32 s14, s13, s11
	s_sub_i32 s8, s8, s14
	s_add_i32 s15, s13, 1
	s_sub_i32 s14, s8, s11
	s_cmp_ge_u32 s8, s11
	s_cselect_b32 s13, s15, s13
	s_cselect_b32 s8, s14, s8
	s_add_i32 s14, s13, 1
	s_cmp_ge_u32 s8, s11
	s_cselect_b32 s8, s14, s13
	s_xor_b32 s8, s8, s12
	s_sub_i32 s8, s8, s12
	s_mul_i32 s10, s8, s10
	s_sub_i32 s3, s3, s10
	s_add_i32 s10, s9, s3
